# v049 plus the 8 rescale-trigger ballots shortened to straight SALU mask logic (no saveexec / cndmask / cmp_ne round trip)
# speedup vs baseline: 1.0057x; 1.0013x over previous
; template <int MODE>
; DI void bias_init(f32x16& s0, f32x16& s1, const TP& tp, float fbm, int hi) {
; #pragma unroll
;     for (int r = 0; r < 16; ++r) {
;         const int kvc = 16 * (r >> 3) + (r & 7);
;         if (MODE == 0) { s0[r] = __builtin_fmaf(-L2E, tp.cs[kvc + 8 * hi], fbm); s1[r] = __builtin_fmaf(-L2E, tp.cs[kvc + 32 + 8 * hi], fbm); }
;         else { s0[r] = __builtin_fmaf(tp.sl, (float)kvc, fbm); s1[r] = __builtin_fmaf(tp.sl, (float)(kvc + 32), fbm); }
;     }
; }
; DI float max3_asm(float a, float b, float c) { float r; asm("v_max3_f32 %0, %1, %2, %3" : "=v"(r) : "v"(a), "v"(b), "v"(c)); return r; }
; template <bool MASK>
; DI float mask_rowmax(f32x16& s0, f32x16& s1, const TP& tp) {
;     if (MASK) {
; #pragma unroll
;         for (int r = 0; r < 16; ++r) {
;             const int kvc = 16 * (r >> 3) + (r & 7);
;             const bool v0 = tp.sel && (kvc <= tp.lim) && (kvc > tp.lim2), v1 = tp.sel && (kvc + 32 <= tp.lim) && (kvc + 32 > tp.lim2);
;             s0[r] = v0 ? s0[r] : -1e30f; s1[r] = v1 ? s1[r] : -1e30f;
;         }
;     }
;     const float seed = __builtin_fminf(s0[15], s1[15]);
;     float ma = seed, mb = seed;
; #pragma unroll
;     for (int r = 0; r < 16; r += 2) { ma = max3_asm(ma, s0[r], s1[r]); mb = max3_asm(mb, s0[r + 1], s1[r + 1]); }
;     const float mx = fmaxf(ma, mb);
;     return fmaxf(mx, __shfl_xor(mx, 32));
; }
; template <int MODE, bool MASK, bool WITH_O>
; DI void attn_tile_t(lptr Kt, lptr Vt, const bf16x8 (&qf)[4], f32x16& o0, f32x16& o1, RowState& rs, const TP& tp, int lane) {
;     const int hi = lane >> 5;
;     f32x16 s0, s1;
;     bias_init<MODE>(s0, s1, tp, tp.fb - rs.mref, hi);
;     qk_acc(Kt, qf, s0, s1, lane);
;     const float mx = mask_rowmax<MASK>(s0, s1, tp);
;     const bool was = rs.seen; rs.seen = was || (mx > -1e29f);
;     const bool trig = (mx > 8.f) || (!was && mx > -1e29f && mx < -8.f);
;     if (__builtin_expect(__any(trig), 0)) {
; DI void slc_unit(const Params& P, lptr L, int u, int tid, int lane, int wid) {
;     ...
;     ATT_LOOP_BEGIN(NTS, false, kb_ + (size_t)((int)list[jt] * 64) * PROJ_LD, vb_ + (size_t)((int)list[jt]) * 64, (const float*)nullptr)
;         const int j = (int)list[jt], kv0 = j * 64;
;         const bool sel = (sm[ql * 8 + (j >> 5)] >> (j & 31)) & 1u;
;         if (__any(sel)) {
.LBB0_613:
	s_add_i32 s1, s0, 0
	s_add_i32 s1, s1, 0x1a104
	v_mov_b32_e32 v0, s1
	ds_read_u8 v0, v0
	s_and_b32 s31, s0, 1
	s_waitcnt lgkmcnt(0)
	v_lshrrev_b32_e32 v34, 3, v0
	v_and_b32_e32 v34, 28, v34
	v_add_u32_e32 v34, v186, v34
	ds_read_b32 v34, v34
	v_and_b32_e32 v35, 31, v0
	s_waitcnt lgkmcnt(0)
	v_lshrrev_b32_e32 v36, v0, v34
	v_bfe_u32 v34, v34, v35, 1
	v_and_b32_e32 v35, 1, v36
	v_cmp_ne_u32_e32 vcc, 0, v34
	v_cmp_eq_u32_e64 s[28:29], 1, v35
	s_cbranch_vccz .LBB0_618
	v_lshl_or_b32 v0, v0, 6, v126
	v_sub_u32_e32 v34, v0, v91
	v_cvt_f32_i32_e32 v34, v34
	s_mov_b32 s0, 2.0
	v_sub_u32_e32 v152, v91, v0
	s_mov_b32 s1, 0x40400000
	v_cmp_lt_i32_e32 vcc, 54, v152
	v_fma_f32 v0, v150, v34, -v101
	s_cmp_eq_u64 vcc, exec
	s_cselect_b64 s[98:99], -1, 0
	s_orn2_b64 s[100:101], s[28:29], s[98:99]
	v_cndmask_b32_e64 v0, v210, v0, s[100:101]
	v_pk_fma_f32 v[36:37], v[94:95], s[0:1], v[0:1] op_sel_hi:[1,1,0]
	s_mov_b32 s0, 4.0
	s_mov_b32 s1, 0x40a00000
	v_pk_fma_f32 v[38:39], v[94:95], s[0:1], v[0:1] op_sel_hi:[1,1,0]
	s_mov_b32 s0, 0x40c00000
	s_mov_b32 s1, 0x40e00000
	v_pk_fma_f32 v[40:41], v[94:95], s[0:1], v[0:1] op_sel_hi:[1,1,0]
	s_mov_b32 s0, 0x41800000
	s_mov_b32 s1, 0x41880000
	v_pk_fma_f32 v[42:43], v[94:95], s[0:1], v[0:1] op_sel_hi:[1,1,0]
	s_mov_b32 s0, 0x41900000
	s_mov_b32 s1, 0x41980000
	v_pk_fma_f32 v[44:45], v[94:95], s[0:1], v[0:1] op_sel_hi:[1,1,0]
	s_mov_b32 s0, 0x41a00000
	s_mul_i32 s33, s31, 0x2400
	s_mov_b32 s1, 0x41a80000
	v_mov_b32_e32 v151, v150
	v_fma_f32 v34, 0, v150, v0
	v_add_f32_e32 v35, v150, v0
	v_pk_fma_f32 v[46:47], v[94:95], s[0:1], v[0:1] op_sel_hi:[1,1,0]
	v_pk_fma_f32 v[48:49], v[94:95], s[18:19], v[0:1] op_sel_hi:[1,1,0]
	v_pk_fma_f32 v[64:65], v[150:151], s[4:5], v[0:1] op_sel_hi:[1,1,0]
	v_pk_fma_f32 v[62:63], v[150:151], s[14:15], v[0:1] op_sel_hi:[1,1,0]
	v_pk_fma_f32 v[60:61], v[150:151], s[16:17], v[0:1] op_sel_hi:[1,1,0]
	v_pk_fma_f32 v[58:59], v[150:151], s[94:95], v[0:1] op_sel_hi:[1,1,0]
	v_pk_fma_f32 v[56:57], v[150:151], s[96:97], v[0:1] op_sel_hi:[1,1,0]
	v_pk_fma_f32 v[54:55], v[150:151], s[84:85], v[0:1] op_sel_hi:[1,1,0]
	v_pk_fma_f32 v[52:53], v[150:151], s[72:73], v[0:1] op_sel_hi:[1,1,0]
	v_pk_fma_f32 v[50:51], v[96:97], s[44:45], v[0:1] op_sel_hi:[1,1,0]
	v_add_u32_e32 v0, s33, v170
	ds_read_b128 v[102:105], v0 offset:4608
	ds_read_b128 v[106:109], v0
	ds_read_b128 v[110:113], v0 offset:32
	ds_read_b128 v[114:117], v0 offset:4640
	ds_read_b128 v[118:121], v0 offset:64
	ds_read_b128 v[158:161], v0 offset:4672
	ds_read_b128 v[162:165], v0 offset:96
	ds_read_b128 v[166:169], v0 offset:4704
	s_setprio 1
	s_waitcnt lgkmcnt(6)
	v_mfma_f32_32x32x16_bf16 v[34:49], v[106:109], v[66:69], v[34:49]
	v_mfma_f32_32x32x16_bf16 v[50:65], v[102:105], v[66:69], v[50:65]
	s_waitcnt lgkmcnt(5)
	v_mfma_f32_32x32x16_bf16 v[34:49], v[110:113], v[70:73], v[34:49]
	s_waitcnt lgkmcnt(4)
	v_mfma_f32_32x32x16_bf16 v[50:65], v[114:117], v[70:73], v[50:65]
	s_waitcnt lgkmcnt(3)
	v_mfma_f32_32x32x16_bf16 v[34:49], v[118:121], v[74:77], v[34:49]
	s_waitcnt lgkmcnt(2)
	v_mfma_f32_32x32x16_bf16 v[50:65], v[158:161], v[74:77], v[50:65]
	s_waitcnt lgkmcnt(1)
	v_mfma_f32_32x32x16_bf16 v[34:49], v[162:165], v[78:81], v[34:49]
	s_waitcnt lgkmcnt(0)
	v_mfma_f32_32x32x16_bf16 v[50:65], v[166:169], v[78:81], v[50:65]
	s_setprio 0
	s_and_b64 vcc, exec, s[98:99]
	s_cbranch_vccz .Lslc_masked
	s_nop 10
	v_max_f32_e32 v252, v65, v65
	v_max_f32_e32 v228, v49, v49
	v_min_f32_e32 v252, v228, v252
	v_max3_f32 v228, v252, v34, v50
	v_max3_f32 v252, v252, v35, v51
	s_mov_b32 s0, 0xefa18f08
	v_max3_f32 v228, v228, v36, v52
	v_max3_f32 v252, v252, v37, v53
	s_nop 0
	v_max3_f32 v228, v228, v38, v54
	v_max3_f32 v252, v252, v39, v55
	s_nop 0
	v_max3_f32 v228, v228, v40, v56
	v_max3_f32 v252, v252, v41, v57
	s_nop 0
	v_max3_f32 v228, v228, v42, v58
	v_max3_f32 v252, v252, v43, v59
	s_nop 0
	v_max3_f32 v228, v228, v44, v60
	v_max3_f32 v252, v252, v45, v61
	s_nop 0
	v_max3_f32 v228, v228, v46, v62
	v_max3_f32 v252, v252, v47, v63
	s_nop 0
	v_max3_f32 v228, v228, v48, v64
	v_max3_f32 v252, v252, v49, v65
	s_nop 0
	v_max_f32_e32 v252, v252, v252
	v_max_f32_e32 v228, v228, v228
	v_max_f32_e32 v252, v228, v252
	ds_bpermute_b32 v228, v149, v252
	s_waitcnt lgkmcnt(0)
	v_max_f32_e32 v228, v228, v228
	v_max_f32_e32 v252, v252, v228
	v_cmp_lt_f32_e64 s[28:29], s0, v252
	s_mov_b32 s0, 0x41000000
	v_cmp_lt_f32_e32 vcc, s0, v252
	s_mov_b32 s0, 0xc1000000
	v_cmp_gt_f32_e64 s[0:1], s0, v252
	s_and_b64 s[0:1], s[0:1], s[28:29]
	s_andn2_b64 s[0:1], s[0:1], s[22:23]
	s_or_b64 s[0:1], s[0:1], vcc
	s_and_b64 vcc, exec, s[0:1]
	s_cbranch_vccnz .Lsf_rare
; DI float exp2_fast(float x) { return __builtin_amdgcn_exp2f(x); }
; template <int MODE, bool MASK, bool WITH_O>
; DI void attn_tile_t(lptr Kt, lptr Vt, const bf16x8 (&qf)[4], f32x16& o0, f32x16& o1, RowState& rs, const TP& tp, int lane) {
;     ...
;     if (!WITH_O) {
;         float sum = 0.f;
; #pragma unroll
;         for (int r = 0; r < 16; ++r) { s0[r] = exp2_fast(s0[r]); s1[r] = exp2_fast(s1[r]); sum += s0[r] + s1[r]; }
;         rs.l += sum;
;     } else {
;         const int i = lane & 31;
;         lptr vp = Vt + i * KPB + hi * 16;
;         float sum = 0.f;
;     ...
;         PV_STEP(s0, 0, 0) PV_STEP(s0, 8, 32) PV_STEP(s1, 0, 64) PV_STEP(s1, 8, 96)
;     ...
;         rs.l += sum;
	v_exp_f32_e32 v252, v34
	v_exp_f32_e32 v103, v35
	v_exp_f32_e32 v111, v36
	v_exp_f32_e32 v105, v37
	v_add_f32_e32 v106, 0, v252
	v_add_f32_e32 v106, v103, v106
	v_add_f32_e32 v104, v111, v106
	v_exp_f32_e32 v106, v38
	v_exp_f32_e32 v107, v39
	v_add_u32_e32 v228, s33, v172
	v_exp_f32_e32 v108, v40
	ds_read_b128 v[236:239], v228 offset:18432
	ds_read_b128 v[240:243], v228 offset:23040
	v_add_f32_e32 v104, v105, v104
	v_exp_f32_e32 v109, v41
	v_add_f32_e32 v104, v106, v104
	v_add_f32_e32 v104, v107, v104
	v_add_f32_e32 v104, v108, v104
	v_add_f32_e32 v110, v109, v104
	v_cvt_pk_bf16_f32 v104, v252, v103
	v_cvt_pk_bf16_f32 v105, v111, v105
	v_cvt_pk_bf16_f32 v106, v106, v107
	v_cvt_pk_bf16_f32 v107, v108, v109
	s_or_b64 s[22:23], s[22:23], s[28:29]
	s_waitcnt lgkmcnt(1)
	v_mfma_f32_32x32x16_bf16 v[18:33], v[236:239], v[104:107], v[18:33]
	s_waitcnt lgkmcnt(0)
	v_mfma_f32_32x32x16_bf16 v[2:17], v[240:243], v[104:107], v[2:17]
	v_exp_f32_e32 v252, v42
	v_exp_f32_e32 v43, v43
	v_exp_f32_e32 v103, v44
	v_exp_f32_e32 v44, v45
	v_add_f32_e32 v229, v252, v110
	v_exp_f32_e32 v45, v46
	v_add_f32_e32 v229, v43, v229
	v_exp_f32_e32 v46, v47
	v_add_f32_e32 v42, v103, v229
	v_exp_f32_e32 v47, v48
	ds_read_b128 v[236:239], v228 offset:18464
	ds_read_b128 v[240:243], v228 offset:23072
	v_add_f32_e32 v42, v44, v42
	v_exp_f32_e32 v48, v49
	v_add_f32_e32 v42, v45, v42
	v_add_f32_e32 v42, v46, v42
	v_add_f32_e32 v42, v47, v42
	v_add_f32_e32 v229, v48, v42
	v_cvt_pk_bf16_f32 v42, v252, v43
	v_cvt_pk_bf16_f32 v43, v103, v44
	v_cvt_pk_bf16_f32 v44, v45, v46
	v_cvt_pk_bf16_f32 v45, v47, v48
	s_waitcnt lgkmcnt(1)
	s_nop 0
	v_mfma_f32_32x32x16_bf16 v[18:33], v[236:239], v[42:45], v[18:33]
	s_waitcnt lgkmcnt(0)
	v_mfma_f32_32x32x16_bf16 v[2:17], v[240:243], v[42:45], v[2:17]
	v_exp_f32_e32 v230, v50
	v_exp_f32_e32 v51, v51
	v_exp_f32_e32 v231, v52
	v_exp_f32_e32 v52, v53
	v_add_f32_e32 v229, v230, v229
	v_exp_f32_e32 v53, v54
	v_add_f32_e32 v229, v51, v229
	v_exp_f32_e32 v54, v55
	v_add_f32_e32 v50, v231, v229
	v_exp_f32_e32 v55, v56
	ds_read_b128 v[42:45], v228 offset:18496
	ds_read_b128 v[46:49], v228 offset:23104
	v_add_f32_e32 v50, v52, v50
	v_exp_f32_e32 v41, v57
	v_add_f32_e32 v50, v53, v50
	v_add_f32_e32 v50, v54, v50
	v_add_f32_e32 v50, v55, v50
	v_add_f32_e32 v56, v41, v50
	v_cvt_pk_bf16_f32 v50, v230, v51
	v_cvt_pk_bf16_f32 v51, v231, v52
	v_cvt_pk_bf16_f32 v52, v53, v54
	v_cvt_pk_bf16_f32 v53, v55, v41
	s_waitcnt lgkmcnt(1)
	s_nop 0
	v_mfma_f32_32x32x16_bf16 v[18:33], v[42:45], v[50:53], v[18:33]
	s_waitcnt lgkmcnt(0)
	v_mfma_f32_32x32x16_bf16 v[2:17], v[46:49], v[50:53], v[2:17]
	v_exp_f32_e32 v38, v58
	v_exp_f32_e32 v34, v59
	v_exp_f32_e32 v0, v60
	v_exp_f32_e32 v35, v61
	v_add_f32_e32 v41, v38, v56
	v_exp_f32_e32 v36, v62
	ds_read_b128 v[42:45], v228 offset:18528
	ds_read_b128 v[46:49], v228 offset:23136
	v_add_f32_e32 v41, v34, v41
	v_exp_f32_e32 v37, v63
	v_exp_f32_e32 v39, v64
	v_exp_f32_e32 v40, v65
	v_add_f32_e32 v41, v0, v41
	v_add_f32_e32 v41, v35, v41
	v_add_f32_e32 v41, v36, v41
	v_add_f32_e32 v41, v37, v41
	v_cvt_pk_bf16_f32 v34, v38, v34
	v_cvt_pk_bf16_f32 v35, v0, v35
	v_cvt_pk_bf16_f32 v36, v36, v37
	v_cvt_pk_bf16_f32 v37, v39, v40
	v_add_f32_e32 v41, v39, v41
	v_add_f32_e32 v41, v40, v41
	s_waitcnt lgkmcnt(1)
	v_mfma_f32_32x32x16_bf16 v[18:33], v[42:45], v[34:37], v[18:33]
	s_waitcnt lgkmcnt(0)
	v_mfma_f32_32x32x16_bf16 v[2:17], v[46:49], v[34:37], v[2:17]
	v_add_f32_e32 v100, v100, v41
	s_branch .LBB0_618
